# P2b S2 second half rewritten: both directions packed (f,b) pairs, lockstep over 16 positions, 3 packed multiplies + 3 bf16 packs per position, d16_hi stores
# speedup vs baseline: 1.0024x; 1.0024x over previous
; #define LAS __attribute__((address_space(3)))
; #define LBAR() do { asm volatile("s_waitcnt lgkmcnt(0)" ::: "memory"); __builtin_amdgcn_s_barrier(); asm volatile("" ::: "memory"); } while (0)
; __device__ __forceinline__ float logsig2(float x) { const float xc = fminf(fmaxf(x, -60.f), 60.f); return -__builtin_amdgcn_logf(1.0f + __builtin_amdgcn_exp2f(-1.4426950408889634f * xc)); }
; __device__ __forceinline__ void gla_prep_phase(LAS unsigned char* lds, const GlaPrepArgs& A, int bid, int G) {
;     ...
;     *(LAS f32x4*)(lds + L_R + (tid >> 3) * 128 + (tid & 7) * 16) = pr;
; #pragma unroll
;     for (int i = 0; i < 4; ++i) { const int id = i * 512 + tid; *(LAS v4u*)(lds + L_V + (id >> 5) * VS_ + (id & 31) * 16) = pv[i]; }
; #pragma unroll
;     for (int i = 0; i < 2; ++i) { const int id = i * 512 + tid; *(LAS v4u*)(lds + L_QGF + (id >> 4) * QS_ + (id & 15) * 16) = pq[i]; *(LAS v4u*)(lds + L_KGF + (id >> 4) * QS_ + (id & 15) * 16) = pk[i]; }
;     LBAR();
;     {
;         const int dd = tid & 127, pg = tid >> 7, d = h * 128 + dd;
;         float wf[16], wb[16];
; #pragma unroll
;         for (int i = 0; i < 16; ++i) { wf[i] = A.w2f[i * 512 + d]; wb[i] = A.w2b[i * 512 + d]; }
;         const float bf_ = A.b2f[d], bb_ = A.b2b[d];
;         float lf[16], lb[16];
; #pragma unroll
;         for (int pp = 0; pp < 16; ++pp) {
;             const LAS float* rr = (const LAS float*)(lds + L_R) + (pg * 16 + pp) * 32;
;             float xf = bf_, xb = bb_;
; #pragma unroll
;             for (int i4 = 0; i4 < 4; ++i4) { const f32x4 a = *(const LAS f32x4*)(rr + 4 * i4), b = *(const LAS f32x4*)(rr + 16 + 4 * i4);
;                 xf += a.x * wf[4 * i4] + a.y * wf[4 * i4 + 1] + a.z * wf[4 * i4 + 2] + a.w * wf[4 * i4 + 3];
;                 xb += b.x * wb[4 * i4] + b.y * wb[4 * i4 + 1] + b.z * wb[4 * i4 + 2] + b.w * wb[4 * i4 + 3]; }
;             lf[pp] = logsig2(xf) * (1.f / 16.f); lb[pp] = logsig2(xb) * (1.f / 16.f);
.LBB0_423:
	s_ashr_i32 s77, s76, 31
	s_lshr_b32 s78, s77, 27
	s_add_i32 s78, s76, s78
	s_ashr_i32 s78, s78, 5
	s_mul_i32 s80, s76, 0x10400
	v_readlane_b32 s88, v253, 48
	s_mul_hi_i32 s79, s76, 0x10400
	v_readlane_b32 s89, v253, 49
	s_add_u32 s88, s88, s80
	s_addc_u32 s89, s89, s79
	s_lshr_b32 s79, s78, 30
	s_add_i32 s79, s78, s79
	s_and_b32 s79, s79, 0x1fffffc
	s_sub_i32 s78, s78, s79
	v_lshl_or_b32 v2, s78, 7, v86
	v_bfe_u32 v3, v70, 5, 1
	v_lshlrev_b32_e32 v248, 2, v2
	v_lshl_add_u32 v2, v3, 14, v248
	v_add_u32_e32 v3, 0x1000, v2
	v_add_u32_e32 v4, 0x2000, v2
	v_add_u32_e32 v5, 0x3000, v2
	s_waitcnt lgkmcnt(0)
	s_waitcnt vmcnt(20)
	ds_write_b128 v107, v[34:37]
	s_waitcnt vmcnt(19)
	ds_write_b128 v108, v[38:41]
	s_waitcnt vmcnt(18)
	ds_write_b128 v109, v[42:45]
	s_waitcnt vmcnt(17)
	ds_write_b128 v110, v[46:49]
	s_waitcnt vmcnt(16)
	ds_write_b128 v111, v[50:53]
	s_waitcnt vmcnt(15)
	ds_write_b128 v112, v[54:57] offset:8192
	s_waitcnt vmcnt(14)
	ds_write_b128 v112, v[58:61] offset:25600
	s_waitcnt vmcnt(13)
	ds_write_b128 v113, v[62:65] offset:8192
	s_waitcnt vmcnt(12)
	ds_write_b128 v113, v[66:69] offset:25600
	global_load_dword v228, v2, s[12:13]
	global_load_dword v229, v2, s[12:13] offset:2048
	global_load_dword v230, v3, s[12:13]
	global_load_dword v231, v3, s[12:13] offset:2048
	global_load_dword v232, v4, s[12:13]
	global_load_dword v233, v4, s[12:13] offset:2048
	global_load_dword v234, v5, s[12:13]
	global_load_dword v235, v5, s[12:13] offset:2048
	global_load_dword v236, v2, s[16:17]
	global_load_dword v237, v2, s[16:17] offset:2048
	global_load_dword v238, v3, s[16:17]
	global_load_dword v239, v3, s[16:17] offset:2048
	global_load_dword v240, v4, s[16:17]
	global_load_dword v241, v4, s[16:17] offset:2048
	global_load_dword v242, v5, s[16:17]
	global_load_dword v243, v5, s[16:17] offset:2048
	global_load_dword v244, v248, s[14:15]
	global_load_dword v246, v248, s[18:19]
	s_waitcnt lgkmcnt(0)
	s_barrier
	ds_read_b128 v[212:215], v87
	ds_read_b128 v[216:219], v87 offset:16
	ds_read_b128 v[220:223], v87 offset:64
	ds_read_b128 v[224:227], v87 offset:80
	s_mov_b32 s100, 0xbfb8aa3b
	s_waitcnt vmcnt(10) lgkmcnt(2)
	v_mfma_f32_32x32x2_f32 v[180:195], v212, v228, 0
	v_mfma_f32_32x32x2_f32 v[180:195], v213, v229, v[180:195]
	v_mfma_f32_32x32x2_f32 v[180:195], v214, v230, v[180:195]
	v_mfma_f32_32x32x2_f32 v[180:195], v215, v231, v[180:195]
	v_mfma_f32_32x32x2_f32 v[180:195], v216, v232, v[180:195]
	v_mfma_f32_32x32x2_f32 v[180:195], v217, v233, v[180:195]
	v_mfma_f32_32x32x2_f32 v[180:195], v218, v234, v[180:195]
	v_mfma_f32_32x32x2_f32 v[180:195], v219, v235, v[180:195]
	s_waitcnt vmcnt(0) lgkmcnt(0)
	v_mfma_f32_32x32x2_f32 v[196:211], v220, v236, 0
	v_mfma_f32_32x32x2_f32 v[196:211], v221, v237, v[196:211]
	s_nop 15
	v_mfma_f32_32x32x2_f32 v[196:211], v222, v238, v[196:211]
	v_pk_add_f32 v[180:181], v[180:181], v[244:245] op_sel_hi:[1,0]
	v_pk_add_f32 v[182:183], v[182:183], v[244:245] op_sel_hi:[1,0]
	v_pk_add_f32 v[184:185], v[184:185], v[244:245] op_sel_hi:[1,0]
	v_pk_add_f32 v[186:187], v[186:187], v[244:245] op_sel_hi:[1,0]
	v_pk_add_f32 v[188:189], v[188:189], v[244:245] op_sel_hi:[1,0]
	v_pk_add_f32 v[190:191], v[190:191], v[244:245] op_sel_hi:[1,0]
	v_pk_add_f32 v[192:193], v[192:193], v[244:245] op_sel_hi:[1,0]
	v_pk_add_f32 v[194:195], v[194:195], v[244:245] op_sel_hi:[1,0]
	v_med3_f32 v180, v180, s66, v170
	v_med3_f32 v181, v181, s66, v170
	v_med3_f32 v182, v182, s66, v170
	v_mfma_f32_32x32x2_f32 v[196:211], v223, v239, v[196:211]
	v_med3_f32 v183, v183, s66, v170
	v_med3_f32 v184, v184, s66, v170
	v_med3_f32 v185, v185, s66, v170
	v_med3_f32 v186, v186, s66, v170
	v_med3_f32 v187, v187, s66, v170
	v_med3_f32 v188, v188, s66, v170
	v_med3_f32 v189, v189, s66, v170
	v_med3_f32 v190, v190, s66, v170
	v_med3_f32 v191, v191, s66, v170
	v_med3_f32 v192, v192, s66, v170
	v_med3_f32 v193, v193, s66, v170
	v_mfma_f32_32x32x2_f32 v[196:211], v224, v240, v[196:211]
	v_med3_f32 v194, v194, s66, v170
	v_med3_f32 v195, v195, s66, v170
	v_pk_mul_f32 v[180:181], v[180:181], s[100:101] op_sel_hi:[1,0]
	v_pk_mul_f32 v[182:183], v[182:183], s[100:101] op_sel_hi:[1,0]
	v_pk_mul_f32 v[184:185], v[184:185], s[100:101] op_sel_hi:[1,0]
	v_pk_mul_f32 v[186:187], v[186:187], s[100:101] op_sel_hi:[1,0]
	v_pk_mul_f32 v[188:189], v[188:189], s[100:101] op_sel_hi:[1,0]
	v_pk_mul_f32 v[190:191], v[190:191], s[100:101] op_sel_hi:[1,0]
	v_pk_mul_f32 v[192:193], v[192:193], s[100:101] op_sel_hi:[1,0]
	v_pk_mul_f32 v[194:195], v[194:195], s[100:101] op_sel_hi:[1,0]
	v_exp_f32_e32 v180, v180
	v_mfma_f32_32x32x2_f32 v[196:211], v225, v241, v[196:211]
	v_exp_f32_e32 v181, v181
	v_exp_f32_e32 v182, v182
	v_exp_f32_e32 v183, v183
	v_exp_f32_e32 v184, v184
	v_exp_f32_e32 v185, v185
	v_exp_f32_e32 v186, v186
	v_exp_f32_e32 v187, v187
	v_exp_f32_e32 v188, v188
	v_exp_f32_e32 v189, v189
	v_exp_f32_e32 v190, v190
	v_exp_f32_e32 v191, v191
	v_mfma_f32_32x32x2_f32 v[196:211], v226, v242, v[196:211]
	v_exp_f32_e32 v192, v192
	v_exp_f32_e32 v193, v193
	v_exp_f32_e32 v194, v194
	v_exp_f32_e32 v195, v195
	v_pk_add_f32 v[180:181], v[180:181], 1.0 op_sel_hi:[1,0]
	v_pk_add_f32 v[182:183], v[182:183], 1.0 op_sel_hi:[1,0]
	v_pk_add_f32 v[184:185], v[184:185], 1.0 op_sel_hi:[1,0]
	v_pk_add_f32 v[186:187], v[186:187], 1.0 op_sel_hi:[1,0]
	v_pk_add_f32 v[188:189], v[188:189], 1.0 op_sel_hi:[1,0]
	v_pk_add_f32 v[190:191], v[190:191], 1.0 op_sel_hi:[1,0]
	v_pk_add_f32 v[192:193], v[192:193], 1.0 op_sel_hi:[1,0]
	v_mfma_f32_32x32x2_f32 v[196:211], v227, v243, v[196:211]
	v_pk_add_f32 v[194:195], v[194:195], 1.0 op_sel_hi:[1,0]
	v_log_f32_e32 v180, v180
	v_log_f32_e32 v181, v181
; #define LAS __attribute__((address_space(3)))
; #define LBAR() do { asm volatile("s_waitcnt lgkmcnt(0)" ::: "memory"); __builtin_amdgcn_s_barrier(); asm volatile("" ::: "memory"); } while (0)
; __device__ __forceinline__ float logsig2(float x) { const float xc = fminf(fmaxf(x, -60.f), 60.f); return -__builtin_amdgcn_logf(1.0f + __builtin_amdgcn_exp2f(-1.4426950408889634f * xc)); }
; __device__ __forceinline__ void gla_prep_phase(LAS unsigned char* lds, const GlaPrepArgs& A, int bid, int G) {
;     ...
;             lf[pp] = logsig2(xf) * (1.f / 16.f); lb[pp] = logsig2(xb) * (1.f / 16.f);
;         }
; #pragma unroll
;         for (int pp = 1; pp < 16; ++pp) lf[pp] += lf[pp - 1];
; #pragma unroll
;     ...
;         LAS float* tot = (LAS float*)(lds + L_TOT);
;         tot[pg * 128 + dd] = lf[15]; tot[512 + pg * 128 + dd] = lb[0];
;         LBAR();
;         float offf = 0.f, offb = 0.f, glf = 0.f, glb = 0.f;
; #pragma unroll
;         for (int g = 0; g < 4; ++g) { const float tf = tot[g * 128 + dd], tb = tot[512 + g * 128 + dd]; glf += tf; glb += tb; if (g < pg) offf += tf; if (g > pg) offb += tb; }
;         const float eglf = __builtin_amdgcn_exp2f(glf), eglb = __builtin_amdgcn_exp2f(glb);
;         if (pg == 0) { float* sc = (float*)(blob + B_SC); sc[dd] = eglf; sc[128 + dd] = eglb; }
	v_log_f32_e32 v182, v182
	v_log_f32_e32 v183, v183
	v_log_f32_e32 v184, v184
	v_log_f32_e32 v185, v185
	v_log_f32_e32 v186, v186
	v_log_f32_e32 v187, v187
	v_log_f32_e32 v188, v188
	v_log_f32_e32 v189, v189
	v_log_f32_e32 v190, v190
	v_log_f32_e32 v191, v191
	v_log_f32_e32 v192, v192
	v_log_f32_e32 v193, v193
	v_log_f32_e32 v194, v194
	v_log_f32_e32 v195, v195
	v_mul_f32_e32 v212, 0xbd800000, v180
	v_fmamk_f32 v214, v181, 0xbd800000, v212
	v_fmamk_f32 v216, v182, 0xbd800000, v214
	v_fmamk_f32 v218, v183, 0xbd800000, v216
	v_fmamk_f32 v220, v184, 0xbd800000, v218
	v_fmamk_f32 v222, v185, 0xbd800000, v220
	v_fmamk_f32 v224, v186, 0xbd800000, v222
	v_fmamk_f32 v226, v187, 0xbd800000, v224
	v_fmamk_f32 v228, v188, 0xbd800000, v226
	v_fmamk_f32 v230, v189, 0xbd800000, v228
	v_fmamk_f32 v232, v190, 0xbd800000, v230
	v_fmamk_f32 v234, v191, 0xbd800000, v232
	v_fmamk_f32 v236, v192, 0xbd800000, v234
	v_fmamk_f32 v238, v193, 0xbd800000, v236
	v_fmamk_f32 v240, v194, 0xbd800000, v238
	v_fmamk_f32 v242, v195, 0xbd800000, v240
	v_pk_add_f32 v[196:197], v[196:197], v[246:247] op_sel_hi:[1,0]
	v_pk_add_f32 v[198:199], v[198:199], v[246:247] op_sel_hi:[1,0]
	v_pk_add_f32 v[200:201], v[200:201], v[246:247] op_sel_hi:[1,0]
	v_pk_add_f32 v[202:203], v[202:203], v[246:247] op_sel_hi:[1,0]
	v_pk_add_f32 v[204:205], v[204:205], v[246:247] op_sel_hi:[1,0]
	v_pk_add_f32 v[206:207], v[206:207], v[246:247] op_sel_hi:[1,0]
	v_pk_add_f32 v[208:209], v[208:209], v[246:247] op_sel_hi:[1,0]
	v_pk_add_f32 v[210:211], v[210:211], v[246:247] op_sel_hi:[1,0]
	v_med3_f32 v196, v196, s66, v170
	v_med3_f32 v197, v197, s66, v170
	v_med3_f32 v198, v198, s66, v170
	v_med3_f32 v199, v199, s66, v170
	v_med3_f32 v200, v200, s66, v170
	v_med3_f32 v201, v201, s66, v170
	v_med3_f32 v202, v202, s66, v170
	v_med3_f32 v203, v203, s66, v170
	v_med3_f32 v204, v204, s66, v170
	v_med3_f32 v205, v205, s66, v170
	v_med3_f32 v206, v206, s66, v170
	v_med3_f32 v207, v207, s66, v170
	v_med3_f32 v208, v208, s66, v170
	v_med3_f32 v209, v209, s66, v170
	v_med3_f32 v210, v210, s66, v170
	v_med3_f32 v211, v211, s66, v170
	v_pk_mul_f32 v[196:197], v[196:197], s[100:101] op_sel_hi:[1,0]
	v_pk_mul_f32 v[198:199], v[198:199], s[100:101] op_sel_hi:[1,0]
	v_pk_mul_f32 v[200:201], v[200:201], s[100:101] op_sel_hi:[1,0]
	v_pk_mul_f32 v[202:203], v[202:203], s[100:101] op_sel_hi:[1,0]
	v_pk_mul_f32 v[204:205], v[204:205], s[100:101] op_sel_hi:[1,0]
	v_pk_mul_f32 v[206:207], v[206:207], s[100:101] op_sel_hi:[1,0]
	v_pk_mul_f32 v[208:209], v[208:209], s[100:101] op_sel_hi:[1,0]
	v_pk_mul_f32 v[210:211], v[210:211], s[100:101] op_sel_hi:[1,0]
	v_exp_f32_e32 v196, v196
	v_exp_f32_e32 v197, v197
	v_exp_f32_e32 v198, v198
	v_exp_f32_e32 v199, v199
	v_exp_f32_e32 v200, v200
	v_exp_f32_e32 v201, v201
	v_exp_f32_e32 v202, v202
	v_exp_f32_e32 v203, v203
	v_exp_f32_e32 v204, v204
	v_exp_f32_e32 v205, v205
	v_exp_f32_e32 v206, v206
	v_exp_f32_e32 v207, v207
	v_exp_f32_e32 v208, v208
	v_exp_f32_e32 v209, v209
	v_exp_f32_e32 v210, v210
	v_exp_f32_e32 v211, v211
	v_pk_add_f32 v[196:197], v[196:197], 1.0 op_sel_hi:[1,0]
	v_pk_add_f32 v[198:199], v[198:199], 1.0 op_sel_hi:[1,0]
	v_pk_add_f32 v[200:201], v[200:201], 1.0 op_sel_hi:[1,0]
	v_pk_add_f32 v[202:203], v[202:203], 1.0 op_sel_hi:[1,0]
	v_pk_add_f32 v[204:205], v[204:205], 1.0 op_sel_hi:[1,0]
	v_pk_add_f32 v[206:207], v[206:207], 1.0 op_sel_hi:[1,0]
	v_pk_add_f32 v[208:209], v[208:209], 1.0 op_sel_hi:[1,0]
	v_pk_add_f32 v[210:211], v[210:211], 1.0 op_sel_hi:[1,0]
	v_log_f32_e32 v211, v211
	v_log_f32_e32 v210, v210
	v_log_f32_e32 v209, v209
	v_log_f32_e32 v208, v208
	v_log_f32_e32 v207, v207
	v_log_f32_e32 v206, v206
	v_log_f32_e32 v205, v205
	v_log_f32_e32 v204, v204
	v_log_f32_e32 v203, v203
	v_log_f32_e32 v202, v202
	v_log_f32_e32 v201, v201
	v_log_f32_e32 v200, v200
	v_log_f32_e32 v199, v199
	v_log_f32_e32 v198, v198
	v_log_f32_e32 v197, v197
	v_log_f32_e32 v196, v196
	v_mul_f32_e32 v243, 0xbd800000, v211
	v_fmamk_f32 v241, v210, 0xbd800000, v243
	v_fmamk_f32 v239, v209, 0xbd800000, v241
	v_fmamk_f32 v237, v208, 0xbd800000, v239
	v_fmamk_f32 v235, v207, 0xbd800000, v237
	v_fmamk_f32 v233, v206, 0xbd800000, v235
	v_fmamk_f32 v231, v205, 0xbd800000, v233
	v_fmamk_f32 v229, v204, 0xbd800000, v231
	v_fmamk_f32 v227, v203, 0xbd800000, v229
	v_fmamk_f32 v225, v202, 0xbd800000, v227
	v_fmamk_f32 v223, v201, 0xbd800000, v225
	v_fmamk_f32 v221, v200, 0xbd800000, v223
	v_fmamk_f32 v219, v199, 0xbd800000, v221
	v_fmamk_f32 v217, v198, 0xbd800000, v219
	v_fmamk_f32 v215, v197, 0xbd800000, v217
	v_fmamk_f32 v213, v196, 0xbd800000, v215
	ds_write_b32 v98, v242
	ds_write_b32 v100, v213 offset:2048
	s_waitcnt lgkmcnt(0)
	s_barrier
	ds_read2st64_b32 v[4:5], v99 offset1:2
	ds_read2st64_b32 v[2:3], v99 offset0:8 offset1:10
	ds_read2st64_b32 v[8:9], v99 offset0:4 offset1:6
	ds_read2st64_b32 v[6:7], v99 offset0:12 offset1:14
	s_waitcnt lgkmcnt(3)
	v_add_f32_e32 v136, 0, v4
	s_waitcnt lgkmcnt(2)
	v_add_f32_e32 v137, 0, v2
	v_add_f32_e32 v2, v136, v5
	v_add_f32_e32 v4, v137, v3
	s_waitcnt lgkmcnt(1)
	v_add_f32_e32 v2, v2, v8
	s_waitcnt lgkmcnt(0)
	v_add_f32_e32 v4, v4, v6
	v_add_f32_e32 v2, v2, v9
	v_add_f32_e32 v138, v4, v7
	v_exp_f32_e32 v4, v2
	v_exp_f32_e32 v2, v138
	s_and_saveexec_b64 s[78:79], s[36:37]
	s_cbranch_execz .LBB0_425
	s_add_u32 s80, s88, 0x8000
	s_addc_u32 s81, s89, 0
	v_lshlrev_b32_e32 v140, 2, v86
	global_store_dword v140, v4, s[80:81]
	global_store_dword v140, v2, s[80:81] offset:512
; #define LAS __attribute__((address_space(3)))
; __device__ __forceinline__ void gla_prep_phase(LAS unsigned char* lds, const GlaPrepArgs& A, int bid, int G) {
;     ...
;         float offf = 0.f, offb = 0.f, glf = 0.f, glb = 0.f;
; #pragma unroll
;         for (int g = 0; g < 4; ++g) { const float tf = tot[g * 128 + dd], tb = tot[512 + g * 128 + dd]; glf += tf; glb += tb; if (g < pg) offf += tf; if (g > pg) offb += tb; }
;         const float eglf = __builtin_amdgcn_exp2f(glf), eglb = __builtin_amdgcn_exp2f(glb);
;         if (pg == 0) { float* sc = (float*)(blob + B_SC); sc[dd] = eglf; sc[128 + dd] = eglb; }
; #pragma unroll
;         for (int pp = 0; pp < 16; ++pp) {
;             const int o = (pg * 16 + pp) * QS_ + dd * 2;
;             const float qv = bf2f(*(const LAS unsigned short*)(lds + L_QGF + o)) * QSCALE, kv = bf2f(*(const LAS unsigned short*)(lds + L_KGF + o));
;             const float ef = __builtin_amdgcn_exp2f(lf[pp] + offf), eb = __builtin_amdgcn_exp2f(lb[pp] + offb);
;             const float rf = __builtin_amdgcn_rcpf(ef), rb = __builtin_amdgcn_rcpf(eb);
.LBB0_425:
	s_or_b64 exec, exec, s[78:79]
	v_cndmask_b32_e64 v136, 0, v136, s[38:39]
	v_cndmask_b32_e64 v137, 0, v137, s[40:41]
	v_add_f32_e32 v5, v136, v5
	v_cndmask_b32_e64 v5, v136, v5, s[42:43]
	v_add_f32_e32 v3, v137, v3
	v_cndmask_b32_e64 v3, 0, v3, s[44:45]
	v_add_f32_e32 v8, v5, v8
	v_cndmask_b32_e64 v5, v5, v8, s[46:47]
	v_add_f32_e32 v3, v3, v6
	v_cndmask_b32_e64 v6, 0, v3, s[48:49]
	v_add_f32_e32 v3, v5, v9
	v_cndmask_b32_e64 v3, v5, v3, s[50:51]
	v_add_f32_e32 v5, v6, v7
	v_cndmask_b32_e64 v5, 0, v5, s[52:53]
	v_mov_b32_e32 v244, v3
	v_mov_b32_e32 v246, v4
	v_mov_b32_e32 v247, v2
	v_mov_b32_e32 v245, v5
	v_add_u32_e32 v248, 0x13000, v114
	v_add_u32_e32 v249, 0x17400, v114
	ds_read_u16 v2, v114 offset:8192
	ds_read_u16 v3, v114 offset:25600
	ds_read_u16 v4, v114 offset:8464
	ds_read_u16 v5, v114 offset:25872
	ds_read_u16 v6, v114 offset:8736
	ds_read_u16 v7, v114 offset:26144
	ds_read_u16 v8, v114 offset:9008
	ds_read_u16 v9, v114 offset:26416
	ds_read_u16 v10, v114 offset:9280
	ds_read_u16 v11, v114 offset:26688
	ds_read_u16 v12, v114 offset:9552
	ds_read_u16 v13, v114 offset:26960
	ds_read_u16 v14, v114 offset:9824
	ds_read_u16 v15, v114 offset:27232
	ds_read_u16 v16, v114 offset:10096
	ds_read_u16 v17, v114 offset:27504
	ds_read_u16 v18, v114 offset:10368
	ds_read_u16 v19, v114 offset:27776
	ds_read_u16 v20, v114 offset:10640
	ds_read_u16 v21, v114 offset:28048
	ds_read_u16 v22, v114 offset:10912
	ds_read_u16 v23, v114 offset:28320
	ds_read_u16 v24, v114 offset:11184
	ds_read_u16 v25, v114 offset:28592
	ds_read_u16 v26, v114 offset:11456
	ds_read_u16 v27, v114 offset:28864
	ds_read_u16 v28, v114 offset:11728
	ds_read_u16 v29, v114 offset:29136
	ds_read_u16 v30, v114 offset:12000
	ds_read_u16 v31, v114 offset:29408
	ds_read_u16 v32, v114 offset:12272
	ds_read_u16 v33, v114 offset:29680
	v_pk_add_f32 v[212:213], v[212:213], v[244:245]
	v_pk_add_f32 v[214:215], v[214:215], v[244:245]
	v_pk_add_f32 v[216:217], v[216:217], v[244:245]
	v_pk_add_f32 v[218:219], v[218:219], v[244:245]
	v_pk_add_f32 v[220:221], v[220:221], v[244:245]
	v_pk_add_f32 v[222:223], v[222:223], v[244:245]
	v_pk_add_f32 v[224:225], v[224:225], v[244:245]
	v_pk_add_f32 v[226:227], v[226:227], v[244:245]
	v_pk_add_f32 v[228:229], v[228:229], v[244:245]
	v_pk_add_f32 v[230:231], v[230:231], v[244:245]
	v_pk_add_f32 v[232:233], v[232:233], v[244:245]
	v_pk_add_f32 v[234:235], v[234:235], v[244:245]
	v_pk_add_f32 v[236:237], v[236:237], v[244:245]
	v_pk_add_f32 v[238:239], v[238:239], v[244:245]
	v_pk_add_f32 v[240:241], v[240:241], v[244:245]
	v_pk_add_f32 v[242:243], v[242:243], v[244:245]
	v_exp_f32_e32 v212, v212
	v_exp_f32_e32 v213, v213
	v_exp_f32_e32 v214, v214
	v_exp_f32_e32 v215, v215
	v_exp_f32_e32 v216, v216
	v_exp_f32_e32 v217, v217
	v_exp_f32_e32 v218, v218
	v_exp_f32_e32 v219, v219
	v_exp_f32_e32 v220, v220
	v_exp_f32_e32 v221, v221
	v_exp_f32_e32 v222, v222
	v_exp_f32_e32 v223, v223
	v_exp_f32_e32 v224, v224
	v_exp_f32_e32 v225, v225
	v_exp_f32_e32 v226, v226
	v_exp_f32_e32 v227, v227
	v_exp_f32_e32 v228, v228
	v_exp_f32_e32 v229, v229
	v_exp_f32_e32 v230, v230
	v_exp_f32_e32 v231, v231
	v_exp_f32_e32 v232, v232
	v_exp_f32_e32 v233, v233
	v_exp_f32_e32 v234, v234
	v_exp_f32_e32 v235, v235
	v_exp_f32_e32 v236, v236
	v_exp_f32_e32 v237, v237
	v_exp_f32_e32 v238, v238
	v_exp_f32_e32 v239, v239
	v_exp_f32_e32 v240, v240
	v_exp_f32_e32 v241, v241
	v_exp_f32_e32 v242, v242
	v_exp_f32_e32 v243, v243
	v_rcp_f32_e32 v180, v212
	v_rcp_f32_e32 v181, v213
	v_rcp_f32_e32 v182, v214
	v_rcp_f32_e32 v183, v215
	v_rcp_f32_e32 v184, v216
	v_rcp_f32_e32 v185, v217
	v_rcp_f32_e32 v186, v218
	v_rcp_f32_e32 v187, v219
	v_rcp_f32_e32 v188, v220
	v_rcp_f32_e32 v189, v221
	v_rcp_f32_e32 v190, v222
	v_rcp_f32_e32 v191, v223
	v_rcp_f32_e32 v192, v224
	v_rcp_f32_e32 v193, v225
	v_rcp_f32_e32 v194, v226
	v_rcp_f32_e32 v195, v227
	v_rcp_f32_e32 v196, v228
	v_rcp_f32_e32 v197, v229
	v_rcp_f32_e32 v198, v230
	v_rcp_f32_e32 v199, v231
	v_rcp_f32_e32 v200, v232
	v_rcp_f32_e32 v201, v233
	v_rcp_f32_e32 v202, v234
	v_rcp_f32_e32 v203, v235
	v_rcp_f32_e32 v204, v236
	v_rcp_f32_e32 v205, v237
	v_rcp_f32_e32 v206, v238
	v_rcp_f32_e32 v207, v239
	v_rcp_f32_e32 v208, v240
	v_rcp_f32_e32 v209, v241
	v_rcp_f32_e32 v210, v242
	v_rcp_f32_e32 v211, v243
	s_waitcnt lgkmcnt(15)
	v_lshlrev_b32_e32 v2, 16, v2
	s_waitcnt lgkmcnt(15)
	v_lshlrev_b32_e32 v3, 16, v3
	s_waitcnt lgkmcnt(15)
	v_lshlrev_b32_e32 v4, 16, v4
	s_waitcnt lgkmcnt(15)
	v_lshlrev_b32_e32 v5, 16, v5
	s_waitcnt lgkmcnt(15)
	v_lshlrev_b32_e32 v6, 16, v6
	s_waitcnt lgkmcnt(15)
	v_lshlrev_b32_e32 v7, 16, v7
	s_waitcnt lgkmcnt(15)
	v_lshlrev_b32_e32 v8, 16, v8
	s_waitcnt lgkmcnt(15)
	v_lshlrev_b32_e32 v9, 16, v9
	s_waitcnt lgkmcnt(15)
	v_lshlrev_b32_e32 v10, 16, v10
	s_waitcnt lgkmcnt(15)
	v_lshlrev_b32_e32 v11, 16, v11
	s_waitcnt lgkmcnt(15)
	v_lshlrev_b32_e32 v12, 16, v12
	s_waitcnt lgkmcnt(15)
	v_lshlrev_b32_e32 v13, 16, v13
	s_waitcnt lgkmcnt(15)
	v_lshlrev_b32_e32 v14, 16, v14
	s_waitcnt lgkmcnt(15)
	v_lshlrev_b32_e32 v15, 16, v15
	s_waitcnt lgkmcnt(15)
	v_lshlrev_b32_e32 v16, 16, v16
	s_waitcnt lgkmcnt(15)
	v_lshlrev_b32_e32 v17, 16, v17
	s_waitcnt lgkmcnt(15)
	v_lshlrev_b32_e32 v18, 16, v18
	s_waitcnt lgkmcnt(14)
	v_lshlrev_b32_e32 v19, 16, v19
	s_waitcnt lgkmcnt(13)
	v_lshlrev_b32_e32 v20, 16, v20
	s_waitcnt lgkmcnt(12)
	v_lshlrev_b32_e32 v21, 16, v21
	s_waitcnt lgkmcnt(11)
	v_lshlrev_b32_e32 v22, 16, v22
	s_waitcnt lgkmcnt(10)
	v_lshlrev_b32_e32 v23, 16, v23
	s_waitcnt lgkmcnt(9)
	v_lshlrev_b32_e32 v24, 16, v24
	s_waitcnt lgkmcnt(8)
	v_lshlrev_b32_e32 v25, 16, v25
	s_waitcnt lgkmcnt(7)
	v_lshlrev_b32_e32 v26, 16, v26
	s_waitcnt lgkmcnt(6)
; #define LAS __attribute__((address_space(3)))
; __device__ __forceinline__ unsigned pkbf(float a, float b) { bf16x2_t v = __builtin_convertvector((f32x2_t){a, b}, bf16x2_t); return __builtin_bit_cast(unsigned, v); }
; __device__ __forceinline__ void gla_prep_phase(LAS unsigned char* lds, const GlaPrepArgs& A, int bid, int G) {
;     ...
;         for (int pp = 0; pp < 16; ++pp) {
;             const int o = (pg * 16 + pp) * QS_ + dd * 2;
;             const float qv = bf2f(*(const LAS unsigned short*)(lds + L_QGF + o)) * QSCALE, kv = bf2f(*(const LAS unsigned short*)(lds + L_KGF + o));
;             const float ef = __builtin_amdgcn_exp2f(lf[pp] + offf), eb = __builtin_amdgcn_exp2f(lb[pp] + offb);
;             const float rf = __builtin_amdgcn_rcpf(ef), rb = __builtin_amdgcn_rcpf(eb);
;             *(LAS unsigned short*)(lds + L_QGF + o) = (unsigned short)(pkbf(qv * ef, 0.f) & 0xffffu);
;             *(LAS unsigned short*)(lds + L_KGF + o) = (unsigned short)(pkbf(kv * rf, 0.f) & 0xffffu);
;             *(LAS unsigned short*)(lds + L_KDF + o) = (unsigned short)(pkbf(kv * rf * eglf, 0.f) & 0xffffu);
;             *(LAS unsigned short*)(lds + L_QGB + o) = (unsigned short)(pkbf(qv * eb, 0.f) & 0xffffu);
;             *(LAS unsigned short*)(lds + L_KGB + o) = (unsigned short)(pkbf(kv * rb, 0.f) & 0xffffu);
;             *(LAS unsigned short*)(lds + L_KDB + o) = (unsigned short)(pkbf(kv * rb * eglb, 0.f) & 0xffffu);
	v_lshlrev_b32_e32 v27, 16, v27
	s_waitcnt lgkmcnt(5)
	v_lshlrev_b32_e32 v28, 16, v28
	s_waitcnt lgkmcnt(4)
	v_lshlrev_b32_e32 v29, 16, v29
	s_waitcnt lgkmcnt(3)
	v_lshlrev_b32_e32 v30, 16, v30
	s_waitcnt lgkmcnt(2)
	v_lshlrev_b32_e32 v31, 16, v31
	s_waitcnt lgkmcnt(1)
	v_lshlrev_b32_e32 v32, 16, v32
	s_waitcnt lgkmcnt(0)
	v_lshlrev_b32_e32 v33, 16, v33
	v_mul_f32_e32 v2, 0x3db504f3, v2
	v_mul_f32_e32 v4, 0x3db504f3, v4
	v_mul_f32_e32 v6, 0x3db504f3, v6
	v_mul_f32_e32 v8, 0x3db504f3, v8
	v_mul_f32_e32 v10, 0x3db504f3, v10
	v_mul_f32_e32 v12, 0x3db504f3, v12
	v_mul_f32_e32 v14, 0x3db504f3, v14
	v_mul_f32_e32 v16, 0x3db504f3, v16
	v_mul_f32_e32 v18, 0x3db504f3, v18
	v_mul_f32_e32 v20, 0x3db504f3, v20
	v_mul_f32_e32 v22, 0x3db504f3, v22
	v_mul_f32_e32 v24, 0x3db504f3, v24
	v_mul_f32_e32 v26, 0x3db504f3, v26
	v_mul_f32_e32 v28, 0x3db504f3, v28
	v_mul_f32_e32 v30, 0x3db504f3, v30
	v_mul_f32_e32 v32, 0x3db504f3, v32
	v_pk_mul_f32 v[212:213], v[212:213], v[2:3] op_sel_hi:[1,0]
	v_pk_mul_f32 v[214:215], v[214:215], v[4:5] op_sel_hi:[1,0]
	v_pk_mul_f32 v[216:217], v[216:217], v[6:7] op_sel_hi:[1,0]
	v_pk_mul_f32 v[218:219], v[218:219], v[8:9] op_sel_hi:[1,0]
	v_pk_mul_f32 v[220:221], v[220:221], v[10:11] op_sel_hi:[1,0]
	v_pk_mul_f32 v[222:223], v[222:223], v[12:13] op_sel_hi:[1,0]
	v_pk_mul_f32 v[224:225], v[224:225], v[14:15] op_sel_hi:[1,0]
	v_pk_mul_f32 v[226:227], v[226:227], v[16:17] op_sel_hi:[1,0]
	v_pk_mul_f32 v[228:229], v[228:229], v[18:19] op_sel_hi:[1,0]
	v_pk_mul_f32 v[230:231], v[230:231], v[20:21] op_sel_hi:[1,0]
	v_pk_mul_f32 v[232:233], v[232:233], v[22:23] op_sel_hi:[1,0]
	v_pk_mul_f32 v[234:235], v[234:235], v[24:25] op_sel_hi:[1,0]
	v_pk_mul_f32 v[236:237], v[236:237], v[26:27] op_sel_hi:[1,0]
	v_pk_mul_f32 v[238:239], v[238:239], v[28:29] op_sel_hi:[1,0]
	v_pk_mul_f32 v[240:241], v[240:241], v[30:31] op_sel_hi:[1,0]
	v_pk_mul_f32 v[242:243], v[242:243], v[32:33] op_sel_hi:[1,0]
	v_pk_mul_f32 v[180:181], v[180:181], v[2:3] op_sel:[0,1] op_sel_hi:[1,1]
	v_pk_mul_f32 v[182:183], v[182:183], v[4:5] op_sel:[0,1] op_sel_hi:[1,1]
	v_pk_mul_f32 v[184:185], v[184:185], v[6:7] op_sel:[0,1] op_sel_hi:[1,1]
	v_pk_mul_f32 v[186:187], v[186:187], v[8:9] op_sel:[0,1] op_sel_hi:[1,1]
	v_pk_mul_f32 v[188:189], v[188:189], v[10:11] op_sel:[0,1] op_sel_hi:[1,1]
	v_pk_mul_f32 v[190:191], v[190:191], v[12:13] op_sel:[0,1] op_sel_hi:[1,1]
	v_pk_mul_f32 v[192:193], v[192:193], v[14:15] op_sel:[0,1] op_sel_hi:[1,1]
	v_pk_mul_f32 v[194:195], v[194:195], v[16:17] op_sel:[0,1] op_sel_hi:[1,1]
	v_pk_mul_f32 v[196:197], v[196:197], v[18:19] op_sel:[0,1] op_sel_hi:[1,1]
	v_pk_mul_f32 v[198:199], v[198:199], v[20:21] op_sel:[0,1] op_sel_hi:[1,1]
	v_pk_mul_f32 v[200:201], v[200:201], v[22:23] op_sel:[0,1] op_sel_hi:[1,1]
	v_pk_mul_f32 v[202:203], v[202:203], v[24:25] op_sel:[0,1] op_sel_hi:[1,1]
	v_pk_mul_f32 v[204:205], v[204:205], v[26:27] op_sel:[0,1] op_sel_hi:[1,1]
	v_pk_mul_f32 v[206:207], v[206:207], v[28:29] op_sel:[0,1] op_sel_hi:[1,1]
	v_pk_mul_f32 v[208:209], v[208:209], v[30:31] op_sel:[0,1] op_sel_hi:[1,1]
	v_pk_mul_f32 v[210:211], v[210:211], v[32:33] op_sel:[0,1] op_sel_hi:[1,1]
	v_pk_mul_f32 v[2:3], v[180:181], v[246:247]
	v_pk_mul_f32 v[4:5], v[182:183], v[246:247]
	v_pk_mul_f32 v[6:7], v[184:185], v[246:247]
	v_pk_mul_f32 v[8:9], v[186:187], v[246:247]
	v_pk_mul_f32 v[10:11], v[188:189], v[246:247]
	v_pk_mul_f32 v[12:13], v[190:191], v[246:247]
	v_pk_mul_f32 v[14:15], v[192:193], v[246:247]
	v_pk_mul_f32 v[16:17], v[194:195], v[246:247]
	v_pk_mul_f32 v[18:19], v[196:197], v[246:247]
	v_pk_mul_f32 v[20:21], v[198:199], v[246:247]
	v_pk_mul_f32 v[22:23], v[200:201], v[246:247]
	v_pk_mul_f32 v[24:25], v[202:203], v[246:247]
	v_pk_mul_f32 v[26:27], v[204:205], v[246:247]
	v_pk_mul_f32 v[28:29], v[206:207], v[246:247]
	v_pk_mul_f32 v[30:31], v[208:209], v[246:247]
	v_pk_mul_f32 v[32:33], v[210:211], v[246:247]
	v_cvt_pk_bf16_f32 v212, v212, v213
	v_cvt_pk_bf16_f32 v214, v214, v215
	v_cvt_pk_bf16_f32 v216, v216, v217
	v_cvt_pk_bf16_f32 v218, v218, v219
	v_cvt_pk_bf16_f32 v220, v220, v221
	v_cvt_pk_bf16_f32 v222, v222, v223
	v_cvt_pk_bf16_f32 v224, v224, v225
	v_cvt_pk_bf16_f32 v226, v226, v227
	v_cvt_pk_bf16_f32 v228, v228, v229
	v_cvt_pk_bf16_f32 v230, v230, v231
	v_cvt_pk_bf16_f32 v232, v232, v233
	v_cvt_pk_bf16_f32 v234, v234, v235
	v_cvt_pk_bf16_f32 v236, v236, v237
	v_cvt_pk_bf16_f32 v238, v238, v239
	v_cvt_pk_bf16_f32 v240, v240, v241
	v_cvt_pk_bf16_f32 v242, v242, v243
	v_cvt_pk_bf16_f32 v180, v180, v181
	v_cvt_pk_bf16_f32 v182, v182, v183
	v_cvt_pk_bf16_f32 v184, v184, v185
	v_cvt_pk_bf16_f32 v186, v186, v187
	v_cvt_pk_bf16_f32 v188, v188, v189
	v_cvt_pk_bf16_f32 v190, v190, v191
	v_cvt_pk_bf16_f32 v192, v192, v193
	v_cvt_pk_bf16_f32 v194, v194, v195
	v_cvt_pk_bf16_f32 v196, v196, v197
	v_cvt_pk_bf16_f32 v198, v198, v199
	v_cvt_pk_bf16_f32 v200, v200, v201
	v_cvt_pk_bf16_f32 v202, v202, v203
	v_cvt_pk_bf16_f32 v204, v204, v205
	v_cvt_pk_bf16_f32 v206, v206, v207
	v_cvt_pk_bf16_f32 v208, v208, v209
	v_cvt_pk_bf16_f32 v210, v210, v211
	v_cvt_pk_bf16_f32 v2, v2, v3
	v_cvt_pk_bf16_f32 v4, v4, v5
	v_cvt_pk_bf16_f32 v6, v6, v7
	v_cvt_pk_bf16_f32 v8, v8, v9
	v_cvt_pk_bf16_f32 v10, v10, v11
	v_cvt_pk_bf16_f32 v12, v12, v13
	v_cvt_pk_bf16_f32 v14, v14, v15
	v_cvt_pk_bf16_f32 v16, v16, v17
	v_cvt_pk_bf16_f32 v18, v18, v19
	v_cvt_pk_bf16_f32 v20, v20, v21
	v_cvt_pk_bf16_f32 v22, v22, v23
	v_cvt_pk_bf16_f32 v24, v24, v25
	v_cvt_pk_bf16_f32 v26, v26, v27
	v_cvt_pk_bf16_f32 v28, v28, v29
	v_cvt_pk_bf16_f32 v30, v30, v31
	v_cvt_pk_bf16_f32 v32, v32, v33
	ds_write_b16 v114, v212 offset:8192
	ds_write_b16_d16_hi v114, v212 offset:60416
; #define LAS __attribute__((address_space(3)))
; __device__ __forceinline__ unsigned pkbf(float a, float b) { bf16x2_t v = __builtin_convertvector((f32x2_t){a, b}, bf16x2_t); return __builtin_bit_cast(unsigned, v); }
; #define LBAR() do { asm volatile("s_waitcnt lgkmcnt(0)" ::: "memory"); __builtin_amdgcn_s_barrier(); asm volatile("" ::: "memory"); } while (0)
; __device__ __forceinline__ void gla_prep_phase(LAS unsigned char* lds, const GlaPrepArgs& A, int bid, int G) {
;     ...
;             *(LAS unsigned short*)(lds + L_QGF + o) = (unsigned short)(pkbf(qv * ef, 0.f) & 0xffffu);
;             *(LAS unsigned short*)(lds + L_KGF + o) = (unsigned short)(pkbf(kv * rf, 0.f) & 0xffffu);
;             *(LAS unsigned short*)(lds + L_KDF + o) = (unsigned short)(pkbf(kv * rf * eglf, 0.f) & 0xffffu);
;             *(LAS unsigned short*)(lds + L_QGB + o) = (unsigned short)(pkbf(qv * eb, 0.f) & 0xffffu);
;             *(LAS unsigned short*)(lds + L_KGB + o) = (unsigned short)(pkbf(kv * rb, 0.f) & 0xffffu);
;             *(LAS unsigned short*)(lds + L_KDB + o) = (unsigned short)(pkbf(kv * rb * eglb, 0.f) & 0xffffu);
;         }
;     }
;     LBAR();
;     { const int un = unit + G; if (un < nunits) GLA_PREFETCH(un); }
	ds_write_b16 v114, v180 offset:25600
	ds_write_b16_d16_hi v248, v180
	ds_write_b16 v114, v2 offset:43008
	ds_write_b16_d16_hi v249, v2
	ds_write_b16 v114, v214 offset:8464
	ds_write_b16_d16_hi v114, v214 offset:60688
	ds_write_b16 v114, v182 offset:25872
	ds_write_b16_d16_hi v248, v182 offset:272
	ds_write_b16 v114, v4 offset:43280
	ds_write_b16_d16_hi v249, v4 offset:272
	ds_write_b16 v114, v216 offset:8736
	ds_write_b16_d16_hi v114, v216 offset:60960
	ds_write_b16 v114, v184 offset:26144
	ds_write_b16_d16_hi v248, v184 offset:544
	ds_write_b16 v114, v6 offset:43552
	ds_write_b16_d16_hi v249, v6 offset:544
	ds_write_b16 v114, v218 offset:9008
	ds_write_b16_d16_hi v114, v218 offset:61232
	ds_write_b16 v114, v186 offset:26416
	ds_write_b16_d16_hi v248, v186 offset:816
	ds_write_b16 v114, v8 offset:43824
	ds_write_b16_d16_hi v249, v8 offset:816
	ds_write_b16 v114, v220 offset:9280
	ds_write_b16_d16_hi v114, v220 offset:61504
	ds_write_b16 v114, v188 offset:26688
	ds_write_b16_d16_hi v248, v188 offset:1088
	ds_write_b16 v114, v10 offset:44096
	ds_write_b16_d16_hi v249, v10 offset:1088
	ds_write_b16 v114, v222 offset:9552
	ds_write_b16_d16_hi v114, v222 offset:61776
	ds_write_b16 v114, v190 offset:26960
	ds_write_b16_d16_hi v248, v190 offset:1360
	ds_write_b16 v114, v12 offset:44368
	ds_write_b16_d16_hi v249, v12 offset:1360
	ds_write_b16 v114, v224 offset:9824
	ds_write_b16_d16_hi v114, v224 offset:62048
	ds_write_b16 v114, v192 offset:27232
	ds_write_b16_d16_hi v248, v192 offset:1632
	ds_write_b16 v114, v14 offset:44640
	ds_write_b16_d16_hi v249, v14 offset:1632
	ds_write_b16 v114, v226 offset:10096
	ds_write_b16_d16_hi v114, v226 offset:62320
	ds_write_b16 v114, v194 offset:27504
	ds_write_b16_d16_hi v248, v194 offset:1904
	ds_write_b16 v114, v16 offset:44912
	ds_write_b16_d16_hi v249, v16 offset:1904
	ds_write_b16 v114, v228 offset:10368
	ds_write_b16_d16_hi v114, v228 offset:62592
	ds_write_b16 v114, v196 offset:27776
	ds_write_b16_d16_hi v248, v196 offset:2176
	ds_write_b16 v114, v18 offset:45184
	ds_write_b16_d16_hi v249, v18 offset:2176
	ds_write_b16 v114, v230 offset:10640
	ds_write_b16_d16_hi v114, v230 offset:62864
	ds_write_b16 v114, v198 offset:28048
	ds_write_b16_d16_hi v248, v198 offset:2448
	ds_write_b16 v114, v20 offset:45456
	ds_write_b16_d16_hi v249, v20 offset:2448
	ds_write_b16 v114, v232 offset:10912
	ds_write_b16_d16_hi v114, v232 offset:63136
	ds_write_b16 v114, v200 offset:28320
	ds_write_b16_d16_hi v248, v200 offset:2720
	ds_write_b16 v114, v22 offset:45728
	ds_write_b16_d16_hi v249, v22 offset:2720
	ds_write_b16 v114, v234 offset:11184
	ds_write_b16_d16_hi v114, v234 offset:63408
	ds_write_b16 v114, v202 offset:28592
	ds_write_b16_d16_hi v248, v202 offset:2992
	ds_write_b16 v114, v24 offset:46000
	ds_write_b16_d16_hi v249, v24 offset:2992
	ds_write_b16 v114, v236 offset:11456
	ds_write_b16_d16_hi v114, v236 offset:63680
	ds_write_b16 v114, v204 offset:28864
	ds_write_b16_d16_hi v248, v204 offset:3264
	ds_write_b16 v114, v26 offset:46272
	ds_write_b16_d16_hi v249, v26 offset:3264
	ds_write_b16 v114, v238 offset:11728
	ds_write_b16_d16_hi v114, v238 offset:63952
	ds_write_b16 v114, v206 offset:29136
	ds_write_b16_d16_hi v248, v206 offset:3536
	ds_write_b16 v114, v28 offset:46544
	ds_write_b16_d16_hi v249, v28 offset:3536
	ds_write_b16 v114, v240 offset:12000
	ds_write_b16_d16_hi v114, v240 offset:64224
	ds_write_b16 v114, v208 offset:29408
	ds_write_b16_d16_hi v248, v208 offset:3808
	ds_write_b16 v114, v30 offset:46816
	ds_write_b16_d16_hi v249, v30 offset:3808
	ds_write_b16 v114, v242 offset:12272
	ds_write_b16_d16_hi v114, v242 offset:64496
	ds_write_b16 v114, v210 offset:29680
	ds_write_b16_d16_hi v248, v210 offset:4080
	ds_write_b16 v114, v32 offset:47088
	ds_write_b16_d16_hi v249, v32 offset:4080
	s_add_i32 s90, s76, s93
	s_waitcnt lgkmcnt(0)
	s_barrier
	s_cmpk_gt_i32 s90, 0x1ff
	s_cselect_b64 s[78:79], -1, 0
	s_and_b64 vcc, exec, s[78:79]
	s_cbranch_vccnz .LBB0_428
	s_ashr_i32 s80, s90, 31
	s_lshr_b32 s81, s80, 27
	s_add_i32 s81, s90, s81
	s_ashr_i32 s91, s81, 5
	s_lshr_b32 s81, s91, 30
	s_add_i32 s81, s91, s81
	s_lshr_b32 s80, s80, 25
	s_and_b32 s81, s81, -4
	s_add_i32 s80, s90, s80
	s_sub_i32 s92, s91, s81
	s_ashr_i32 s80, s80, 7
	s_lshl_b32 s91, s91, 11
	s_ashr_i32 s81, s80, 31
	s_sub_i32 s91, s67, s91
	s_lshl_b64 s[80:81], s[80:81], 11
	s_ashr_i32 s93, s91, 31
	s_add_u32 s80, s80, s91
	s_addc_u32 s81, s81, s93
	v_lshl_add_u64 v[2:3], s[80:81], 0, v[72:73]
	s_lshl_b32 vcc_lo, s92, 8
	v_lshlrev_b64 v[2:3], 8, v[2:3]
	s_ashr_i32 vcc_hi, vcc_lo, 31
	v_lshl_add_u64 v[6:7], s[80:81], 0, v[74:75]
	v_lshl_add_u64 v[2:3], v[94:95], 0, v[2:3]
	v_lshl_add_u64 v[4:5], vcc, 1, v[90:91]
	v_lshlrev_b64 v[6:7], 11, v[6:7]
	v_lshl_add_u64 v[6:7], v[4:5], 0, v[6:7]
	global_load_dwordx4 v[34:37], v[2:3], off offset:128
	global_load_dwordx4 v[38:41], v[6:7], off
	v_lshl_add_u64 v[2:3], s[80:81], 0, v[76:77]
	v_lshlrev_b64 v[2:3], 11, v[2:3]
	v_lshl_add_u64 v[6:7], s[80:81], 0, v[78:79]
	v_lshl_add_u64 v[2:3], v[4:5], 0, v[2:3]
	v_lshlrev_b64 v[6:7], 11, v[6:7]
	v_lshl_add_u64 v[6:7], v[4:5], 0, v[6:7]
	global_load_dwordx4 v[42:45], v[2:3], off
	global_load_dwordx4 v[46:49], v[6:7], off
	v_lshl_add_u64 v[2:3], s[80:81], 0, v[80:81]
	s_lshl_b32 vcc_lo, s92, 7
	v_lshlrev_b64 v[2:3], 11, v[2:3]
	s_ashr_i32 vcc_hi, vcc_lo, 31
	v_lshl_add_u64 v[6:7], s[80:81], 0, v[82:83]
	v_lshl_add_u64 v[2:3], v[4:5], 0, v[2:3]
	v_lshl_add_u64 v[4:5], vcc, 1, v[92:93]
	v_lshlrev_b64 v[6:7], 11, v[6:7]
	v_lshl_add_u64 v[6:7], v[4:5], 0, v[6:7]
	global_load_dwordx4 v[50:53], v[2:3], off
	global_load_dwordx4 v[54:57], v[6:7], off
	v_lshl_add_u64 v[2:3], s[80:81], 0, v[84:85]
	v_lshlrev_b64 v[2:3], 11, v[2:3]
	v_lshl_add_u64 v[2:3], v[4:5], 0, v[2:3]
	global_load_dwordx4 v[58:61], v[6:7], off offset:1024
	global_load_dwordx4 v[62:65], v[2:3], off
	global_load_dwordx4 v[66:69], v[2:3], off offset:1024
	v_readlane_b32 s93, v254, 17
	s_mov_b64 s[80:81], -1
	s_and_b64 vcc, exec, s[70:71]
	s_cbranch_vccnz .LBB0_429
